# v3 plus: gemm3 meta-row (skinny) items publish their act rows with write-through (sc1) stores + drained vmcnt instead of plain stores + buffer_wbl2 release fence per item
# baseline (speedup 1.0000x reference)
; #define LAS __attribute__((address_space(3)))
; DEV unsigned cvt_pk_bf16(float lo, float hi) { unsigned r; asm("v_cvt_pk_bf16_f32 %0, %1, %2" : "=v"(r) : "v"(lo), "v"(hi)); return r; }
; DEV float row_rs(const float* ss, int row) { const f32x4 s4 = *(const f32x4*)(ss + (size_t)row * 4); return rsqrtf(((s4[0] + s4[1]) + (s4[2] + s4[3])) * (1.0f / 1024.0f) + EPS); }
; DEV void skinny_reduce(LAS unsigned char* lds, int wid, int lane, const f32x4 (&acc)[16], f32x4& a0, f32x4& a1) {
;     ...
;     for (int nb = 0; nb < 16; ++nb) *(LAS f32x4*)(lds + ((wid * 16 + nb) * 64 + lane) * 16) = acc[nb];
;     __syncthreads();
;     a0 = (f32x4){0.f, 0.f, 0.f, 0.f}; a1 = a0;
; #pragma unroll
;     for (int w = 0; w < 8; ++w) { a0 += *(const LAS f32x4*)(lds + ((w * 16 + 2 * wid) * 64 + lane) * 16); a1 += *(const LAS f32x4*)(lds + ((w * 16 + 2 * wid + 1) * 64 + lane) * 16); }
;     __syncthreads();
;     DEV void skinny(f32x4 a0, f32x4 a1, int mb, int pn, LAS unsigned char*) const {
;         EPI_IDS
;         const int row = TX + mb * 16 + fr;
;         const float rs = row_rs(ss, row);
;         const f32x4 g = a0 * rs, u = a1 * rs;
;         float o[4];
; #pragma unroll
;         for (int j = 0; j < 4; ++j) o[j] = g[j] * __builtin_amdgcn_rcpf(1.0f + __expf(-g[j])) * u[j];
;         *(u32x2*)(act + (size_t)row * DFF + pn * 128 + (wid & 3) * 32 + fq * 8 + (wid >> 2) * 4) = (u32x2){cvt_pk_bf16(o[0], o[1]), cvt_pk_bf16(o[2], o[3])};
;         asm volatile("s_waitcnt vmcnt(0)" ::: "memory");
;         __syncthreads();
;         if (tid == 0) { __builtin_amdgcn_fence(__ATOMIC_RELEASE, "agent"); asm volatile("s_waitcnt vmcnt(0)" ::: "memory"); (void)__hip_atomic_fetch_add(mcnt, 1u, __ATOMIC_RELAXED, __HIP_MEMORY_SCOPE_AGENT); }
.LBB0_1321:
	s_or_b64 exec, exec, s[8:9]
	v_lshlrev_b32_e32 v65, 4, v71
	v_lshlrev_b32_e32 v64, 14, v70
	v_and_b32_e32 v65, 0x3f0, v65
	v_add3_u32 v64, 0, v64, v65
	ds_write_b128 v64, v[60:63]
	ds_write_b128 v64, v[56:59] offset:1024
	ds_write_b128 v64, v[52:55] offset:2048
	ds_write_b128 v64, v[48:51] offset:3072
	ds_write_b128 v64, v[44:47] offset:4096
	ds_write_b128 v64, v[40:43] offset:5120
	ds_write_b128 v64, v[36:39] offset:6144
	ds_write_b128 v64, v[32:35] offset:7168
	ds_write_b128 v64, v[28:31] offset:8192
	ds_write_b128 v64, v[24:27] offset:9216
	ds_write_b128 v64, v[20:23] offset:10240
	ds_write_b128 v64, v[16:19] offset:11264
	ds_write_b128 v64, v[12:15] offset:12288
	ds_write_b128 v64, v[8:11] offset:13312
	ds_write_b128 v64, v[4:7] offset:14336
	ds_write_b128 v64, v[0:3] offset:15360
	v_lshlrev_b32_e32 v0, 11, v70
	v_add3_u32 v12, 0, v0, v65
	s_waitcnt lgkmcnt(0)
	s_barrier
	ds_read_b128 v[0:3], v12
	v_mov_b32_e32 v14, v188
	v_readlane_b32 s8, v253, 52
	v_readlane_b32 s9, v253, 53
	s_waitcnt lgkmcnt(0)
	v_pk_add_f32 v[4:5], v[2:3], 0 op_sel_hi:[1,0]
	v_pk_add_f32 v[6:7], v[0:1], 0 op_sel_hi:[1,0]
	ds_read_b128 v[0:3], v12 offset:1024
	s_waitcnt lgkmcnt(0)
	v_pk_add_f32 v[8:9], v[2:3], 0 op_sel_hi:[1,0]
	v_pk_add_f32 v[10:11], v[0:1], 0 op_sel_hi:[1,0]
	ds_read_b128 v[0:3], v12 offset:16384
	s_waitcnt lgkmcnt(0)
	v_pk_add_f32 v[4:5], v[4:5], v[2:3]
	v_pk_add_f32 v[6:7], v[6:7], v[0:1]
	ds_read_b128 v[0:3], v12 offset:17408
	s_waitcnt lgkmcnt(0)
	v_pk_add_f32 v[8:9], v[8:9], v[2:3]
	v_pk_add_f32 v[10:11], v[10:11], v[0:1]
	ds_read_b128 v[0:3], v12 offset:32768
	s_waitcnt lgkmcnt(0)
	v_pk_add_f32 v[4:5], v[4:5], v[2:3]
	v_pk_add_f32 v[6:7], v[6:7], v[0:1]
	ds_read_b128 v[0:3], v12 offset:33792
	s_waitcnt lgkmcnt(0)
	v_pk_add_f32 v[8:9], v[8:9], v[2:3]
	v_pk_add_f32 v[10:11], v[10:11], v[0:1]
	ds_read_b128 v[0:3], v12 offset:49152
	s_waitcnt lgkmcnt(0)
	v_pk_add_f32 v[4:5], v[4:5], v[2:3]
	v_pk_add_f32 v[6:7], v[6:7], v[0:1]
	ds_read_b128 v[0:3], v12 offset:50176
	s_waitcnt lgkmcnt(0)
	v_pk_add_f32 v[10:11], v[10:11], v[0:1]
	v_add_u32_e32 v0, 0x10000, v12
	v_pk_add_f32 v[8:9], v[8:9], v[2:3]
	ds_read_b128 v[0:3], v0
	s_waitcnt lgkmcnt(0)
	v_pk_add_f32 v[6:7], v[6:7], v[0:1]
	v_add_u32_e32 v0, 0x10400, v12
	v_pk_add_f32 v[4:5], v[4:5], v[2:3]
	ds_read_b128 v[0:3], v0
	s_waitcnt lgkmcnt(0)
	v_pk_add_f32 v[10:11], v[10:11], v[0:1]
	v_add_u32_e32 v0, 0x14000, v12
	v_pk_add_f32 v[8:9], v[8:9], v[2:3]
	ds_read_b128 v[0:3], v0
	s_waitcnt lgkmcnt(0)
	v_pk_add_f32 v[6:7], v[6:7], v[0:1]
	v_add_u32_e32 v0, 0x14400, v12
	v_pk_add_f32 v[4:5], v[4:5], v[2:3]
	ds_read_b128 v[0:3], v0
	s_waitcnt lgkmcnt(0)
	v_pk_add_f32 v[10:11], v[10:11], v[0:1]
	v_add_u32_e32 v0, 0x18000, v12
	v_pk_add_f32 v[8:9], v[8:9], v[2:3]
	ds_read_b128 v[0:3], v0
	s_waitcnt lgkmcnt(0)
	v_pk_add_f32 v[6:7], v[6:7], v[0:1]
	v_add_u32_e32 v0, 0x18400, v12
	v_pk_add_f32 v[4:5], v[4:5], v[2:3]
	ds_read_b128 v[0:3], v0
	s_waitcnt lgkmcnt(0)
	v_pk_add_f32 v[10:11], v[10:11], v[0:1]
	v_add_u32_e32 v0, 0x1c000, v12
	v_pk_add_f32 v[8:9], v[8:9], v[2:3]
	ds_read_b128 v[0:3], v0
	s_waitcnt lgkmcnt(0)
	v_pk_add_f32 v[6:7], v[6:7], v[0:1]
	v_add_u32_e32 v0, 0x1c400, v12
	v_pk_add_f32 v[4:5], v[4:5], v[2:3]
	ds_read_b128 v[0:3], v0
	s_waitcnt lgkmcnt(0)
	s_barrier
	v_pk_add_f32 v[10:11], v[10:11], v[0:1]
	v_and_or_b32 v194, v14, 15, s28
	v_lshl_add_u64 v[0:1], v[194:195], 4, s[8:9]
	v_pk_add_f32 v[8:9], v[8:9], v[2:3]
	global_load_dwordx4 v[0:3], v[0:1], off
	s_waitcnt vmcnt(0)
	v_mov_b32_e32 v12, v1
	v_mov_b32_e32 v13, v2
	v_mov_b32_e32 v1, v3
	v_pk_add_f32 v[0:1], v[12:13], v[0:1]
	s_nop 0
	v_add_f32_e32 v0, v0, v1
	v_fmamk_f32 v0, v0, 0x3a800000, v189
	v_cmp_gt_f32_e32 vcc, s24, v0
	v_mul_f32_e32 v1, 0x4b800000, v0
	s_nop 0
	v_cndmask_b32_e32 v0, v0, v1, vcc
	v_rsq_f32_e32 v0, v0
	s_nop 0
	v_mul_f32_e32 v1, 0x45800000, v0
	v_cndmask_b32_e32 v0, v0, v1, vcc
	v_pk_mul_f32 v[2:3], v[4:5], v[0:1] op_sel_hi:[1,0]
	v_pk_mul_f32 v[4:5], v[6:7], v[0:1] op_sel_hi:[1,0]
	v_pk_mul_f32 v[6:7], v[8:9], v[0:1] op_sel_hi:[1,0]
	v_mul_f32_e32 v8, 0xbfb8aa3b, v4
	v_exp_f32_e32 v8, v8
	v_pk_mul_f32 v[0:1], v[10:11], v[0:1] op_sel_hi:[1,0]
	v_cmp_eq_u32_e32 vcc, 0, v14
	v_add_f32_e32 v8, 1.0, v8
	v_rcp_f32_e32 v8, v8
	s_nop 0
	v_mul_f32_e32 v4, v4, v8
	v_mul_f32_e32 v0, v0, v4
	v_mul_f32_e32 v4, 0xbfb8aa3b, v5
	v_exp_f32_e32 v4, v4
	s_nop 0
	v_add_f32_e32 v4, 1.0, v4
	v_rcp_f32_e32 v4, v4
	s_nop 0
	v_mul_f32_e32 v4, v5, v4
	v_mul_f32_e32 v1, v1, v4
	v_mul_f32_e32 v4, 0xbfb8aa3b, v2
	v_exp_f32_e32 v4, v4
	v_cvt_pk_bf16_f32 v0, v0, v1
	s_nop 0
	v_add_f32_e32 v4, 1.0, v4
	v_rcp_f32_e32 v4, v4
	s_nop 0
	v_mul_f32_e32 v2, v2, v4
	v_mul_f32_e32 v4, 0xbfb8aa3b, v3
	v_exp_f32_e32 v4, v4
	v_mul_f32_e32 v2, v6, v2
	v_add_f32_e32 v4, 1.0, v4
	v_rcp_f32_e32 v4, v4
	s_nop 0
	v_mul_f32_e32 v3, v3, v4
	v_mul_f32_e32 v3, v7, v3
	v_cvt_pk_bf16_f32 v1, v2, v3
	v_mov_b64_e32 v[2:3], s[70:71]
	v_mad_u64_u32 v[2:3], s[8:9], v194, s33, v[2:3]
	s_lshl_b32 s8, s7, 7
	s_ashr_i32 s9, s8, 31
	v_lshl_add_u64 v[2:3], s[8:9], 1, v[2:3]
	v_and_b32_e32 v194, 0xc0, v14
	v_ashrrev_i32_e32 v4, 6, v14
	v_lshl_add_u64 v[2:3], v[2:3], 0, v[194:195]
	v_and_b32_e32 v194, 48, v14
	v_and_b32_e32 v4, -4, v4
	v_lshl_add_u64 v[2:3], v[2:3], 0, v[194:195]
	v_ashrrev_i32_e32 v5, 31, v4
	v_lshl_add_u64 v[2:3], v[4:5], 1, v[2:3]
	global_store_dwordx2 v[2:3], v[0:1], off sc1
	s_waitcnt vmcnt(0)
	s_barrier
	s_and_saveexec_b64 s[8:9], vcc
	s_cbranch_execz .LBB0_1316
	s_mov_b64 s[36:37], exec
	v_mbcnt_lo_u32_b32 v0, s36, 0
	s_waitcnt vmcnt(0)
	s_waitcnt vmcnt(0)
	v_mbcnt_hi_u32_b32 v0, s37, v0
	v_cmp_eq_u32_e32 vcc, 0, v0
	s_and_b64 s[28:29], exec, vcc
	s_mov_b64 exec, s[28:29]
	s_cbranch_execz .LBB0_1316
	s_bcnt1_i32_b64 s7, s[36:37]
	v_mov_b32_e32 v0, s7
	global_atomic_add v195, v0, s[0:1]
	s_branch .LBB0_1316

; #define LAS __attribute__((address_space(3)))
; DEV unsigned cvt_pk_bf16(float lo, float hi) { unsigned r; asm("v_cvt_pk_bf16_f32 %0, %1, %2" : "=v"(r) : "v"(lo), "v"(hi)); return r; }
; DEV float row_rs(const float* ss, int row) { const f32x4 s4 = *(const f32x4*)(ss + (size_t)row * 4); return rsqrtf(((s4[0] + s4[1]) + (s4[2] + s4[3])) * (1.0f / 1024.0f) + EPS); }
; DEV void skinny_reduce(LAS unsigned char* lds, int wid, int lane, const f32x4 (&acc)[16], f32x4& a0, f32x4& a1) {
;     ...
;     for (int nb = 0; nb < 16; ++nb) *(LAS f32x4*)(lds + ((wid * 16 + nb) * 64 + lane) * 16) = acc[nb];
;     __syncthreads();
;     a0 = (f32x4){0.f, 0.f, 0.f, 0.f}; a1 = a0;
; #pragma unroll
;     for (int w = 0; w < 8; ++w) { a0 += *(const LAS f32x4*)(lds + ((w * 16 + 2 * wid) * 64 + lane) * 16); a1 += *(const LAS f32x4*)(lds + ((w * 16 + 2 * wid + 1) * 64 + lane) * 16); }
;     __syncthreads();
;     DEV void skinny(f32x4 a0, f32x4 a1, int mb, int pn, LAS unsigned char*) const {
;         EPI_IDS
;         const int row = TX + mb * 16 + fr;
;         const float rs = row_rs(ss, row);
;         const f32x4 g = a0 * rs, u = a1 * rs;
;         float o[4];
; #pragma unroll
;         for (int j = 0; j < 4; ++j) o[j] = g[j] * __builtin_amdgcn_rcpf(1.0f + __expf(-g[j])) * u[j];
;         *(u32x2*)(act + (size_t)row * DFF + pn * 128 + (wid & 3) * 32 + fq * 8 + (wid >> 2) * 4) = (u32x2){cvt_pk_bf16(o[0], o[1]), cvt_pk_bf16(o[2], o[3])};
;         asm volatile("s_waitcnt vmcnt(0)" ::: "memory");
;         __syncthreads();
;         if (tid == 0) { __builtin_amdgcn_fence(__ATOMIC_RELEASE, "agent"); asm volatile("s_waitcnt vmcnt(0)" ::: "memory"); (void)__hip_atomic_fetch_add(mcnt, 1u, __ATOMIC_RELAXED, __HIP_MEMORY_SCOPE_AGENT); }
.LBB0_1349:
	s_or_b64 exec, exec, s[8:9]
	v_lshlrev_b32_e32 v65, 4, v71
	v_lshlrev_b32_e32 v64, 14, v70
	v_and_b32_e32 v65, 0x3f0, v65
	v_add3_u32 v64, 0, v64, v65
	ds_write_b128 v64, v[60:63]
	ds_write_b128 v64, v[56:59] offset:1024
	ds_write_b128 v64, v[52:55] offset:2048
	ds_write_b128 v64, v[48:51] offset:3072
	ds_write_b128 v64, v[44:47] offset:4096
	ds_write_b128 v64, v[40:43] offset:5120
	ds_write_b128 v64, v[36:39] offset:6144
	ds_write_b128 v64, v[32:35] offset:7168
	ds_write_b128 v64, v[28:31] offset:8192
	ds_write_b128 v64, v[24:27] offset:9216
	ds_write_b128 v64, v[20:23] offset:10240
	ds_write_b128 v64, v[16:19] offset:11264
	ds_write_b128 v64, v[12:15] offset:12288
	ds_write_b128 v64, v[8:11] offset:13312
	ds_write_b128 v64, v[4:7] offset:14336
	ds_write_b128 v64, v[0:3] offset:15360
	v_lshlrev_b32_e32 v0, 11, v70
	v_add3_u32 v12, 0, v0, v65
	s_waitcnt lgkmcnt(0)
	s_barrier
	ds_read_b128 v[0:3], v12
	v_mov_b32_e32 v14, v188
	v_readlane_b32 s8, v253, 52
	v_readlane_b32 s9, v253, 53
	s_lshl_b32 s4, s4, 8
	s_waitcnt lgkmcnt(0)
	v_pk_add_f32 v[4:5], v[2:3], 0 op_sel_hi:[1,0]
	v_pk_add_f32 v[6:7], v[0:1], 0 op_sel_hi:[1,0]
	ds_read_b128 v[0:3], v12 offset:1024
	s_waitcnt lgkmcnt(0)
	v_pk_add_f32 v[8:9], v[2:3], 0 op_sel_hi:[1,0]
	v_pk_add_f32 v[10:11], v[0:1], 0 op_sel_hi:[1,0]
	ds_read_b128 v[0:3], v12 offset:16384
	s_waitcnt lgkmcnt(0)
	v_pk_add_f32 v[4:5], v[4:5], v[2:3]
	v_pk_add_f32 v[6:7], v[6:7], v[0:1]
	ds_read_b128 v[0:3], v12 offset:17408
	s_waitcnt lgkmcnt(0)
	v_pk_add_f32 v[8:9], v[8:9], v[2:3]
	v_pk_add_f32 v[10:11], v[10:11], v[0:1]
	ds_read_b128 v[0:3], v12 offset:32768
	s_waitcnt lgkmcnt(0)
	v_pk_add_f32 v[4:5], v[4:5], v[2:3]
	v_pk_add_f32 v[6:7], v[6:7], v[0:1]
	ds_read_b128 v[0:3], v12 offset:33792
	s_waitcnt lgkmcnt(0)
	v_pk_add_f32 v[8:9], v[8:9], v[2:3]
	v_pk_add_f32 v[10:11], v[10:11], v[0:1]
	ds_read_b128 v[0:3], v12 offset:49152
	s_waitcnt lgkmcnt(0)
	v_pk_add_f32 v[4:5], v[4:5], v[2:3]
	v_pk_add_f32 v[6:7], v[6:7], v[0:1]
	ds_read_b128 v[0:3], v12 offset:50176
	s_waitcnt lgkmcnt(0)
	v_pk_add_f32 v[10:11], v[10:11], v[0:1]
	v_add_u32_e32 v0, 0x10000, v12
	v_pk_add_f32 v[8:9], v[8:9], v[2:3]
	ds_read_b128 v[0:3], v0
	s_waitcnt lgkmcnt(0)
	v_pk_add_f32 v[6:7], v[6:7], v[0:1]
	v_add_u32_e32 v0, 0x10400, v12
	v_pk_add_f32 v[4:5], v[4:5], v[2:3]
	ds_read_b128 v[0:3], v0
	s_waitcnt lgkmcnt(0)
	v_pk_add_f32 v[10:11], v[10:11], v[0:1]
	v_add_u32_e32 v0, 0x14000, v12
	v_pk_add_f32 v[8:9], v[8:9], v[2:3]
	ds_read_b128 v[0:3], v0
	s_waitcnt lgkmcnt(0)
	v_pk_add_f32 v[6:7], v[6:7], v[0:1]
	v_add_u32_e32 v0, 0x14400, v12
	v_pk_add_f32 v[4:5], v[4:5], v[2:3]
	ds_read_b128 v[0:3], v0
	s_waitcnt lgkmcnt(0)
	v_pk_add_f32 v[10:11], v[10:11], v[0:1]
	v_add_u32_e32 v0, 0x18000, v12
	v_pk_add_f32 v[8:9], v[8:9], v[2:3]
	ds_read_b128 v[0:3], v0
	s_waitcnt lgkmcnt(0)
	v_pk_add_f32 v[6:7], v[6:7], v[0:1]
	v_add_u32_e32 v0, 0x18400, v12
	v_pk_add_f32 v[4:5], v[4:5], v[2:3]
	ds_read_b128 v[0:3], v0
	s_waitcnt lgkmcnt(0)
	v_pk_add_f32 v[10:11], v[10:11], v[0:1]
	v_add_u32_e32 v0, 0x1c000, v12
	v_pk_add_f32 v[8:9], v[8:9], v[2:3]
	ds_read_b128 v[0:3], v0
	s_waitcnt lgkmcnt(0)
	v_pk_add_f32 v[6:7], v[6:7], v[0:1]
	v_add_u32_e32 v0, 0x1c400, v12
	v_pk_add_f32 v[4:5], v[4:5], v[2:3]
	ds_read_b128 v[0:3], v0
	s_waitcnt lgkmcnt(0)
	s_barrier
	v_pk_add_f32 v[10:11], v[10:11], v[0:1]
	v_and_or_b32 v194, v14, 15, s28
	v_lshl_add_u64 v[0:1], v[194:195], 4, s[8:9]
	v_pk_add_f32 v[8:9], v[8:9], v[2:3]
	global_load_dwordx4 v[0:3], v[0:1], off
	s_waitcnt vmcnt(0)
	v_mov_b32_e32 v12, v1
	v_mov_b32_e32 v13, v2
	v_mov_b32_e32 v1, v3
	v_pk_add_f32 v[0:1], v[12:13], v[0:1]
	s_nop 0
	v_add_f32_e32 v0, v0, v1
	v_fmamk_f32 v0, v0, 0x3a800000, v189
	v_cmp_gt_f32_e32 vcc, s24, v0
	v_mul_f32_e32 v1, 0x4b800000, v0
	s_nop 0
	v_cndmask_b32_e32 v0, v0, v1, vcc
	v_rsq_f32_e32 v0, v0
	s_nop 0
	v_mul_f32_e32 v1, 0x45800000, v0
	v_cndmask_b32_e32 v0, v0, v1, vcc
	v_pk_mul_f32 v[2:3], v[4:5], v[0:1] op_sel_hi:[1,0]
	v_pk_mul_f32 v[4:5], v[6:7], v[0:1] op_sel_hi:[1,0]
	v_pk_mul_f32 v[6:7], v[8:9], v[0:1] op_sel_hi:[1,0]
	v_mul_f32_e32 v8, 0xbfb8aa3b, v4
	v_exp_f32_e32 v8, v8
	v_pk_mul_f32 v[0:1], v[10:11], v[0:1] op_sel_hi:[1,0]
	v_cmp_eq_u32_e32 vcc, 0, v14
	v_add_f32_e32 v8, 1.0, v8
	v_rcp_f32_e32 v8, v8
	s_nop 0
	v_mul_f32_e32 v4, v4, v8
	v_mul_f32_e32 v0, v0, v4
	v_mul_f32_e32 v4, 0xbfb8aa3b, v5
	v_exp_f32_e32 v4, v4
	s_nop 0
	v_add_f32_e32 v4, 1.0, v4
	v_rcp_f32_e32 v4, v4
	s_nop 0
	v_mul_f32_e32 v4, v5, v4
	v_mul_f32_e32 v1, v1, v4
	v_mul_f32_e32 v4, 0xbfb8aa3b, v2
	v_exp_f32_e32 v4, v4
	v_cvt_pk_bf16_f32 v0, v0, v1
	s_nop 0
	v_add_f32_e32 v4, 1.0, v4
	v_rcp_f32_e32 v4, v4
	s_nop 0
	v_mul_f32_e32 v2, v2, v4
	v_mul_f32_e32 v4, 0xbfb8aa3b, v3
	v_exp_f32_e32 v4, v4
	v_mul_f32_e32 v2, v6, v2
	v_add_f32_e32 v4, 1.0, v4
	v_rcp_f32_e32 v4, v4
	s_nop 0
	v_mul_f32_e32 v3, v3, v4
	v_mul_f32_e32 v3, v7, v3
	v_cvt_pk_bf16_f32 v1, v2, v3
	v_mov_b64_e32 v[2:3], s[70:71]
	v_mad_u64_u32 v[2:3], s[8:9], v194, s33, v[2:3]
	v_lshl_add_u64 v[2:3], v[2:3], 0, s[4:5]
	v_and_b32_e32 v194, 0xc0, v14
	v_ashrrev_i32_e32 v4, 6, v14
	v_lshl_add_u64 v[2:3], v[2:3], 0, v[194:195]
	v_and_b32_e32 v194, 48, v14
	v_and_b32_e32 v4, -4, v4
	v_lshl_add_u64 v[2:3], v[2:3], 0, v[194:195]
	v_ashrrev_i32_e32 v5, 31, v4
	v_lshl_add_u64 v[2:3], v[4:5], 1, v[2:3]
	global_store_dwordx2 v[2:3], v[0:1], off sc1
	s_waitcnt vmcnt(0)
	s_barrier
	s_and_saveexec_b64 s[8:9], vcc
	s_cbranch_execz .LBB0_1344
	s_mov_b64 s[36:37], exec
	v_mbcnt_lo_u32_b32 v0, s36, 0
	s_waitcnt vmcnt(0)
	s_waitcnt vmcnt(0)
	v_mbcnt_hi_u32_b32 v0, s37, v0
	v_cmp_eq_u32_e32 vcc, 0, v0
	s_and_b64 s[28:29], exec, vcc
	s_mov_b64 exec, s[28:29]
	s_cbranch_execz .LBB0_1344
	s_bcnt1_i32_b64 s4, s[36:37]
	v_mov_b32_e32 v0, s4
	global_atomic_add v195, v0, s[0:1]
	s_branch .LBB0_1344
